# v26 + attention items: one static s_setprio 1 for waves 4-7 (younger half), reset at item end
# speedup vs baseline: 1.0024x; 1.0003x over previous
; __global__ void __launch_bounds__(512) fwd_megakernel(Params P) {
;     ...
;         const int NATT = 768, NCONV = 512;
;         for (int it = blockIdx.x; it < NATT + NCONV; it += gridDim.x) { if (it < NATT) attn_item(P, s, it, lds); else conv_item(P, s, it - NATT, lds); }
.LBB0_381:
	s_setprio 0
	v_readlane_b32 s0, v253, 6
	s_add_i32 s2, s2, s0
	s_cmpk_gt_i32 s2, 0x4ff
	s_cbranch_scc1 .LBB0_885

; #define LAS __attribute__((address_space(3)))
; #define GAS __attribute__((address_space(1)))
; __device__ __forceinline__ void stage_kv(const u16* src_base_  , int b, int L, int dil, int r, int m0, int M, LAS unsigned char* img, const float* gk, int ht) {
;   const GAS u16* src_base = (const GAS u16*)src_base_;
;   const int dch = ht & 15;
;   float gv[8];
;   if (gk) {
; #pragma unroll
;     for (int e = 0; e < 8; ++e) gv[e] = gk[dch * 8 + e];
;   }
; __global__ void __launch_bounds__(512) fwd_megakernel(Params P) {
;     ...
;         const int NATT = 768, NCONV = 512;
;         for (int it = blockIdx.x; it < NATT + NCONV; it += gridDim.x) { if (it < NATT) attn_item(P, s, it, lds); else conv_item(P, s, it - NATT, lds); }
.LBB0_523:
	s_movk_i32 s85, 0x110
	s_and_b64 vcc, exec, s[0:1]
	s_cbranch_vccz .LBB0_381
	v_readfirstlane_b32 s4, v215
	s_cmpk_gt_u32 s4, 0xff
	s_cbranch_scc0 .Latprio
	s_setprio 1
.Latprio:
	v_readlane_b32 s4, v253, 0
	v_readlane_b32 s5, v253, 1
	v_readlane_b32 s6, v253, 2
	v_readlane_b32 s7, v253, 3
	s_mov_b64 s[4:5], s[6:7]
	v_mov_b32_e32 v107, v215
	v_readlane_b32 s0, v253, 23
	v_readlane_b32 s1, v253, 24
	v_and_b32_e32 v77, 15, v107
	v_readfirstlane_b32 s72, v107
	s_andn2_b64 vcc, exec, s[0:1]
	v_lshlrev_b32_e32 v8, 3, v77
	s_cbranch_vccnz .LBB0_526
	v_lshlrev_b32_e32 v4, 2, v8
	global_load_dwordx4 v[0:3], v4, s[48:49] offset:16
	s_nop 0
	global_load_dwordx4 v[4:7], v4, s[48:49]
	s_branch .LBB0_527
